# E10 + persistent ones operand for the row-sum MFMA, single v_max at row-max head, MLA rope DMAs split between wave halves (5 pieces per wave)
# speedup vs baseline: 1.0210x; 1.0002x over previous
; #define LAS __attribute__((address_space(3)))
;     __device__ __forceinline__ unsigned char* ws() const { return (unsigned char*)raw(25); }
; template <int TYPE> __device__ __forceinline__ void attn_unit(LAS unsigned char* lds, const AttnUnit& U) {
;     ...
;     f32x16 o0 = {}, o1 = {}, o2 = {}, negm = {}, p0 = {}, p1 = {};
;     u32x4 pw[4] = {};
;     const bf16x8 ones = {0x3F80, 0x3F80, 0x3F80, 0x3F80, 0x3F80, 0x3F80, 0x3F80, 0x3F80};
; __device__ __forceinline__ void attn_phase(const Ctx& a, LAS unsigned char* lds) {
;     unsigned char* ws = a.ws();
;     const bf16* PROJ = (const bf16*)(ws + WS_PROJ); const bf16* QM = (const bf16*)(ws + WS_QM); const bf16* KV = (const bf16*)(ws + WS_KV); const bf16* KROPE = (const bf16*)(ws + WS_KROPE);
;     const bf16* FKS = (const bf16*)(ws + WS_FKS); const bf16* FVS = (const bf16*)(ws + WS_FVS); const float* LKB = (const float*)(ws + WS_LK); bf16* OB = (bf16*)(ws + WS_XN);
;     unsigned* qctr = (unsigned*)(ws + WS_QCTR);
;     const int myx = (int)(__builtin_amdgcn_s_getreg((3 << 11) | 20) & 7u);
;     LAS int* slot = (LAS int*)(lds + PTR_OFF + 256);
;     int qoff = 0;
.LBB0_635:
	v_writelane_b32 v227, s92, 7
	s_nop 1
	v_writelane_b32 v227, s93, 8
	v_writelane_b32 v227, s91, 9
	v_writelane_b32 v227, s90, 10
	v_writelane_b32 v227, s89, 11
	v_writelane_b32 v227, s88, 12
	v_writelane_b32 v227, s87, 13
	v_writelane_b32 v227, s83, 14
	v_writelane_b32 v227, s86, 15
	s_nop 1
	v_writelane_b32 v227, s87, 16
	v_writelane_b32 v227, s84, 17
	s_nop 1
	v_writelane_b32 v227, s85, 18
	v_writelane_b32 v227, s82, 19
	v_writelane_b32 v227, s81, 20
	s_or_b64 exec, exec, s[0:1]
	s_add_i32 s0, 0, 0x200c8
	v_mov_b32_e32 v0, s0
	s_waitcnt lgkmcnt(0)
	s_barrier
	ds_read_b64 v[0:1], v0
	s_mov_b32 s97, 0
	s_getreg_b32 s16, hwreg(HW_REG_XCC_ID, 0, 4)
	v_mov_b32_e32 v185, 1
	v_mov_b32_e32 v248, 0x3f803f80
	v_mov_b32_e32 v249, 0x3f803f80
	v_mov_b32_e32 v250, 0x3f803f80
	v_mov_b32_e32 v251, 0x3f803f80
	s_mov_b32 s90, 0x42200000
	s_waitcnt lgkmcnt(0)
	v_readfirstlane_b32 s1, v0
	v_readfirstlane_b32 s0, v1
	s_add_u32 s2, s1, 0x13497000
	v_writelane_b32 v227, s2, 21
	s_addc_u32 s2, s0, 0
	v_writelane_b32 v227, s2, 22
	s_add_u32 s2, s1, 0x295f7000
	v_writelane_b32 v227, s2, 23
	s_addc_u32 s2, s0, 0
	v_writelane_b32 v227, s2, 24
	s_add_u32 s2, s1, 0x2f657000
	v_writelane_b32 v227, s2, 25
	s_addc_u32 s2, s0, 0
	v_writelane_b32 v227, s2, 26
	s_add_u32 s2, s1, 0x2d93000
	v_writelane_b32 v227, s2, 27
	s_addc_u32 s2, s0, 0
	v_writelane_b32 v227, s2, 28
	s_add_u32 s2, s1, 0xe437000
	v_writelane_b32 v227, s2, 29
	s_addc_u32 s2, s0, 0
	v_writelane_b32 v227, s2, 30
	s_add_u32 s2, s1, 0x10467000
	v_writelane_b32 v227, s2, 31
	s_addc_u32 s2, s0, 0
	v_writelane_b32 v227, s2, 32
	s_add_u32 s2, s1, 0x2990000
	v_writelane_b32 v227, s2, 33
	s_addc_u32 s2, s0, 0
	v_writelane_b32 v227, s2, 34
	s_add_u32 s2, s1, 0x3397000
	v_writelane_b32 v227, s2, 35
	s_addc_u32 s2, s0, 0
	v_writelane_b32 v227, s2, 36
	s_add_u32 s2, s1, 0x3b6d7000
	s_addc_u32 s3, s0, 0
	v_writelane_b32 v227, s2, 37
	v_mov_b32_e32 v1, 0
	s_mov_b32 s76, 0x3f803f80
	v_writelane_b32 v227, s3, 38
	s_add_u32 s2, s1, 0x2890000
	s_addc_u32 s3, s0, 0
	v_writelane_b32 v227, s2, 39
	s_add_i32 s0, 0, 0x20100
	v_mov_b32_e32 v186, s0
	v_writelane_b32 v227, s3, 40
	v_writelane_b32 v227, s0, 41
	s_add_i32 s0, 0, 0x14100
	v_writelane_b32 v227, s0, 42
	s_add_i32 s0, 0, 0x14200
	v_writelane_b32 v227, s0, 43
	s_add_i32 s0, 0, 0x14300
	v_writelane_b32 v227, s0, 44
	s_add_i32 s0, 0, 0x1000
	v_writelane_b32 v227, s0, 45
	s_add_i32 s0, 0, 0x800
	s_add_i32 s93, 0, 0x14000
	v_writelane_b32 v227, s0, 46
	s_movk_i32 s37, 0x7fff
	v_mov_b32_e32 v187, 0x100
	v_mov_b32_e32 v188, 0xff800000
	v_mov_b32_e32 v189, 0x2000
	v_mov_b32_e32 v190, 0
	v_writelane_b32 v227, s93, 47
	v_writelane_b32 v227, s16, 48
	s_branch .LBB0_637

; #define LAS __attribute__((address_space(3)))
; template <int TYPE> __device__ __forceinline__ void attn_unit(LAS unsigned char* lds, const AttnUnit& U) {
;     ...
;         float mt; A_ROWMAX(s0, s1, mt);
;         bool resc = false;
;         if (__any(mt > THR)) {
;             const float dl = fmaxf(mt, 0.f); mref += dl;
; #pragma unroll
;             for (int r = 0; r < 16; ++r) { s0[r] -= dl; s1[r] -= dl; if (TYPE == 0) negm[r] = -mref; }
;             if (hi == 0) wsf[r32] = __builtin_amdgcn_exp2f(-dl);
;             resc = true;
;         }
;         A_PV(sk2, true, s0, s1);
;         if (resc) {
;             asm volatile("s_waitcnt lgkmcnt(0)" ::: "memory");
; #pragma unroll
;             for (int g = 0; g < 4; ++g) { const f32x4 al = *(const LAS f32x4*)(wsf + 8 * g + 4 * hi);
; #pragma unroll
;                 for (int i = 0; i < 4; ++i) { o0[4 * g + i] *= al[i]; o1[4 * g + i] *= al[i]; o2[4 * g + i] *= al[i]; } }
;             asm volatile("s_waitcnt lgkmcnt(0)" ::: "memory");
.LBB0_678:
	s_lshl_b32 s6, s77, 13
	s_add_i32 s6, s6, 0xc000
	v_add_u32_e32 v0, s6, v174
	v_add_u32_e32 v14, s6, v173
	ds_read_b64_tr_b16 v[2:3], v0
	ds_read_b64_tr_b16 v[4:5], v0 offset:1024
	ds_read_b64_tr_b16 v[6:7], v14
	ds_read_b64_tr_b16 v[8:9], v14 offset:1024
	ds_read_b64_tr_b16 v[178:179], v0 offset:2048
	ds_read_b64_tr_b16 v[180:181], v0 offset:3072
	ds_read_b64_tr_b16 v[192:193], v14 offset:2048
	ds_read_b64_tr_b16 v[194:195], v14 offset:3072
	v_mfma_f32_32x32x16_bf16 v[48:63], v[148:151], v[248:251], v[48:63]
	v_max_f32_e32 v236, v96, v97
	v_max3_f32 v237, v98, v99, v113
	v_max3_f32 v236, v236, v112, v114
	v_max3_f32 v236, v236, v115, v100
	v_max3_f32 v237, v237, v102, v103
	s_waitcnt lgkmcnt(6)
	v_mfma_f32_32x32x16_bf16 v[32:47], v[148:151], v[2:5], v[32:47]
	v_max3_f32 v236, v236, v101, v116
	v_max3_f32 v237, v237, v118, v119
	v_max3_f32 v236, v236, v117, v104
	v_max3_f32 v237, v237, v106, v107
	v_max3_f32 v236, v236, v105, v120
	v_max3_f32 v237, v237, v122, v123
	s_waitcnt lgkmcnt(4)
	v_mfma_f32_32x32x16_bf16 v[16:31], v[148:151], v[6:9], v[16:31]
	v_max3_f32 v236, v236, v121, v108
	v_max3_f32 v237, v237, v110, v111
	v_max3_f32 v236, v236, v109, v124
	v_max3_f32 v237, v237, v126, v127
	v_max3_f32 v236, v236, v125, v237
	v_cmp_lt_f32_e32 vcc, s90, v236
	s_cmp_lg_u64 vcc, 0
	s_cselect_b64 s[72:73], -1, 0
	s_cbranch_vccz .LBB0_682
	v_mov_b32_e32 v237, v236
	s_nop 1
	v_permlane32_swap_b32_e32 v236, v237
	v_max_f32_e32 v237, v237, v237
	v_max_f32_e32 v236, v236, v236
	v_max_f32_e32 v236, v236, v237
	v_max_f32_e32 v236, v236, v236
	v_max_f32_e32 v236, 0, v236
	s_and_saveexec_b64 s[78:79], s[4:5]
	v_exp_f32_e64 v237, -v236
	ds_write_b32 v176, v237
	s_or_b64 exec, exec, s[78:79]
	v_sub_f32_e32 v111, v111, v236
	v_sub_f32_e32 v110, v110, v236
	v_sub_f32_e32 v109, v109, v236
	v_sub_f32_e32 v108, v108, v236
	v_sub_f32_e32 v107, v107, v236
	v_sub_f32_e32 v106, v106, v236
	v_sub_f32_e32 v105, v105, v236
	v_sub_f32_e32 v104, v104, v236
	v_sub_f32_e32 v103, v103, v236
	v_sub_f32_e32 v102, v102, v236
	v_sub_f32_e32 v101, v101, v236
	v_sub_f32_e32 v100, v100, v236
	v_sub_f32_e32 v99, v99, v236
	v_sub_f32_e32 v98, v98, v236
	v_sub_f32_e32 v97, v97, v236
	v_sub_f32_e32 v96, v96, v236
	v_sub_f32_e32 v127, v127, v236
	v_sub_f32_e32 v126, v126, v236
	v_sub_f32_e32 v125, v125, v236
	v_sub_f32_e32 v124, v124, v236
	v_sub_f32_e32 v123, v123, v236
	v_sub_f32_e32 v122, v122, v236
	v_sub_f32_e32 v121, v121, v236
	v_sub_f32_e32 v120, v120, v236
	v_sub_f32_e32 v119, v119, v236
	v_sub_f32_e32 v118, v118, v236
	v_sub_f32_e32 v117, v117, v236
	v_sub_f32_e32 v116, v116, v236
	v_sub_f32_e32 v115, v115, v236
	v_sub_f32_e32 v114, v114, v236
	v_sub_f32_e32 v113, v113, v236
	v_sub_f32_e32 v112, v112, v236
	v_add_f32_e32 v160, v160, v236
.LBB0_682:
	v_exp_f32_e32 v64, v96
	v_exp_f32_e32 v65, v97
	v_exp_f32_e32 v80, v112
	v_mfma_f32_32x32x16_bf16 v[48:63], v[152:155], v[248:251], v[48:63]
	ds_read_b64_tr_b16 v[2:3], v0 offset:4096
	ds_read_b64_tr_b16 v[4:5], v0 offset:5120
	ds_read_b64_tr_b16 v[6:7], v14 offset:4096
	ds_read_b64_tr_b16 v[8:9], v14 offset:5120
	v_exp_f32_e32 v66, v98
	v_exp_f32_e32 v81, v113
	v_exp_f32_e32 v82, v114
	v_exp_f32_e32 v67, v99
	s_waitcnt lgkmcnt(6)
	v_mfma_f32_32x32x16_bf16 v[32:47], v[152:155], v[178:181], v[32:47]
	v_exp_f32_e32 v83, v115
	v_exp_f32_e32 v68, v100
	v_exp_f32_e32 v69, v101
	v_exp_f32_e32 v84, v116
	s_waitcnt lgkmcnt(4)
	v_mfma_f32_32x32x16_bf16 v[16:31], v[152:155], v[192:195], v[16:31]
	v_exp_f32_e32 v70, v102
	v_exp_f32_e32 v85, v117
	v_exp_f32_e32 v86, v118
	v_exp_f32_e32 v71, v103
	v_mfma_f32_32x32x16_bf16 v[48:63], v[156:159], v[248:251], v[48:63]
	ds_read_b64_tr_b16 v[228:229], v0 offset:6144
	ds_read_b64_tr_b16 v[230:231], v0 offset:7168
	ds_read_b64_tr_b16 v[232:233], v14 offset:6144
	ds_read_b64_tr_b16 v[234:235], v14 offset:7168
	v_exp_f32_e32 v87, v119
	v_exp_f32_e32 v72, v104
	v_exp_f32_e32 v73, v105
	s_waitcnt lgkmcnt(6)
	v_mfma_f32_32x32x16_bf16 v[32:47], v[156:159], v[2:5], v[32:47]
	v_exp_f32_e32 v88, v120
	v_exp_f32_e32 v74, v106
	v_exp_f32_e32 v89, v121
	s_waitcnt lgkmcnt(4)
	v_mfma_f32_32x32x16_bf16 v[16:31], v[156:159], v[6:9], v[16:31]
	v_exp_f32_e32 v90, v122
	v_exp_f32_e32 v75, v107
	v_exp_f32_e32 v91, v123
	v_mfma_f32_32x32x16_bf16 v[48:63], v[144:147], v[248:251], v[48:63]
	v_exp_f32_e32 v76, v108
	v_exp_f32_e32 v77, v109
	v_exp_f32_e32 v92, v124
	s_waitcnt lgkmcnt(2)
	v_mfma_f32_32x32x16_bf16 v[32:47], v[144:147], v[228:231], v[32:47]
	v_exp_f32_e32 v78, v110
	v_exp_f32_e32 v93, v125
	v_exp_f32_e32 v94, v126
	s_waitcnt lgkmcnt(0)
	v_mfma_f32_32x32x16_bf16 v[16:31], v[144:147], v[232:235], v[16:31]
	v_exp_f32_e32 v79, v111
	v_exp_f32_e32 v95, v127
	s_andn2_b64 vcc, exec, s[72:73]
	s_cbranch_vccnz .LBB0_684
	s_waitcnt lgkmcnt(0)
	ds_read_b128 v[2:5], v177 offset:96
	ds_read_b128 v[6:9], v177 offset:64
	ds_read_b128 v[10:13], v177 offset:32
	ds_read_b128 v[96:99], v177
	s_waitcnt lgkmcnt(0)
	s_waitcnt lgkmcnt(3)
	v_pk_mul_f32 v[46:47], v[46:47], v[4:5]
	s_waitcnt lgkmcnt(2)
	v_pk_mul_f32 v[42:43], v[42:43], v[8:9]
	s_waitcnt lgkmcnt(1)
	v_pk_mul_f32 v[38:39], v[38:39], v[12:13]
	s_waitcnt lgkmcnt(0)
	v_pk_mul_f32 v[34:35], v[34:35], v[98:99]
	v_pk_mul_f32 v[44:45], v[44:45], v[2:3]
	v_pk_mul_f32 v[40:41], v[40:41], v[6:7]
	v_pk_mul_f32 v[36:37], v[36:37], v[10:11]
	v_pk_mul_f32 v[32:33], v[32:33], v[96:97]
	v_pk_mul_f32 v[30:31], v[30:31], v[4:5]
	v_pk_mul_f32 v[26:27], v[26:27], v[8:9]
	v_pk_mul_f32 v[22:23], v[22:23], v[12:13]
	v_pk_mul_f32 v[18:19], v[18:19], v[98:99]
	v_pk_mul_f32 v[28:29], v[28:29], v[2:3]
	v_pk_mul_f32 v[24:25], v[24:25], v[6:7]
	v_pk_mul_f32 v[20:21], v[20:21], v[10:11]
	v_pk_mul_f32 v[16:17], v[16:17], v[96:97]
	v_pk_mul_f32 v[62:63], v[62:63], v[4:5]
	v_pk_mul_f32 v[58:59], v[58:59], v[8:9]
	v_pk_mul_f32 v[54:55], v[54:55], v[12:13]
	v_pk_mul_f32 v[50:51], v[50:51], v[98:99]
	v_pk_mul_f32 v[60:61], v[60:61], v[2:3]
	v_pk_mul_f32 v[56:57], v[56:57], v[6:7]
	v_pk_mul_f32 v[52:53], v[52:53], v[10:11]
	v_pk_mul_f32 v[48:49], v[48:49], v[96:97]

.Lmla_skip_aux1:
	s_min_i32 s88, s90, s75
	s_cmp_gt_u32 s75, s90
	s_cselect_b64 s[72:73], -1, 0
	s_lshl_b32 s96, s88, 6
	s_mul_i32 s88, s96, s74
	s_mov_b32 s89, s97
	s_lshl_b64 s[88:89], s[88:89], 1
	s_add_u32 s88, s80, s88
	s_addc_u32 s89, s81, s89
	s_and_b32 s90, s90, 3
	s_mulk_i32 s90, 0x3000
	v_cndmask_b32_e64 v0, v195, v194, s[72:73]
	s_add_i32 s91, s90, s82
	s_mov_b32 m0, s91
	s_nop 0
	global_load_lds_dwordx4 v0, s[88:89]
	s_lshl_b64 s[88:89], s[96:97], 6
	s_add_u32 s88, s40, s88
	s_addc_u32 s89, s41, s89
	v_cndmask_b32_e64 v0, v198, v197, s[72:73]
	s_add_i32 s72, s90, s2
	v_readfirstlane_b32 s73, v184
	s_cmp_lt_u32 s73, 0x100
	s_cbranch_scc1 .Lmla_skip_aux2
	s_mov_b32 m0, s72
	s_nop 0
	global_load_lds_dwordx4 v0, s[88:89]

; #define LAS __attribute__((address_space(3)))
; template <int TYPE> __device__ __forceinline__ void attn_unit(LAS unsigned char* lds, const AttnUnit& U) {
;     ...
;         float mt; A_ROWMAX(s0, s1, mt);
;         bool resc = false;
;         if (__any(mt > THR)) {
;             const float dl = fmaxf(mt, 0.f); mref += dl;
; #pragma unroll
;             for (int r = 0; r < 16; ++r) { s0[r] -= dl; s1[r] -= dl; if (TYPE == 0) negm[r] = -mref; }
;             if (hi == 0) wsf[r32] = __builtin_amdgcn_exp2f(-dl);
;             resc = true;
;         }
;         A_PV(sk2, true, s0, s1);
;         if (resc) {
;             asm volatile("s_waitcnt lgkmcnt(0)" ::: "memory");
; #pragma unroll
;             for (int g = 0; g < 4; ++g) { const f32x4 al = *(const LAS f32x4*)(wsf + 8 * g + 4 * hi);
; #pragma unroll
;                 for (int i = 0; i < 4; ++i) { o0[4 * g + i] *= al[i]; o1[4 * g + i] *= al[i]; o2[4 * g + i] *= al[i]; } }
;             asm volatile("s_waitcnt lgkmcnt(0)" ::: "memory");
.LBB0_750:
	s_lshl_b32 s77, s77, 13
	s_add_i32 s77, s77, 0xc000
	v_add_u32_e32 v0, s77, v200
	v_add_u32_e32 v14, s77, v201
	ds_read_b64_tr_b16 v[2:3], v0
	ds_read_b64_tr_b16 v[4:5], v0 offset:1024
	ds_read_b64_tr_b16 v[6:7], v14
	ds_read_b64_tr_b16 v[8:9], v14 offset:1024
	ds_read_b64_tr_b16 v[212:213], v0 offset:2048
	ds_read_b64_tr_b16 v[214:215], v0 offset:3072
	ds_read_b64_tr_b16 v[216:217], v14 offset:2048
	ds_read_b64_tr_b16 v[218:219], v14 offset:3072
	v_mfma_f32_32x32x16_bf16 v[48:63], v[172:175], v[248:251], v[48:63]
	v_max_f32_e32 v236, v128, v129
	v_max3_f32 v237, v130, v131, v113
	v_max3_f32 v236, v236, v112, v114
	v_max3_f32 v236, v236, v115, v132
	v_max3_f32 v237, v237, v134, v135
	s_waitcnt lgkmcnt(6)
	v_mfma_f32_32x32x16_bf16 v[32:47], v[172:175], v[2:5], v[32:47]
	v_max3_f32 v236, v236, v133, v116
	v_max3_f32 v237, v237, v118, v119
	v_max3_f32 v236, v236, v117, v136
	v_max3_f32 v237, v237, v138, v139
	v_max3_f32 v236, v236, v137, v120
	v_max3_f32 v237, v237, v122, v123
	s_waitcnt lgkmcnt(4)
	v_mfma_f32_32x32x16_bf16 v[16:31], v[172:175], v[6:9], v[16:31]
	v_max3_f32 v236, v236, v121, v140
	v_max3_f32 v237, v237, v142, v143
	v_max3_f32 v236, v236, v141, v124
	v_max3_f32 v237, v237, v126, v127
	v_max3_f32 v236, v236, v125, v237
	v_cmp_lt_f32_e32 vcc, s90, v236
	s_cmp_lg_u64 vcc, 0
	s_cselect_b64 s[72:73], -1, 0
	s_cbranch_vccz .LBB0_754
	v_mov_b32_e32 v237, v236
	s_nop 1
	v_permlane32_swap_b32_e32 v236, v237
	v_max_f32_e32 v237, v237, v237
	v_max_f32_e32 v236, v236, v236
	v_max_f32_e32 v236, v236, v237
	v_max_f32_e32 v236, v236, v236
	v_max_f32_e32 v236, 0, v236
	s_and_saveexec_b64 s[78:79], s[4:5]
	v_exp_f32_e64 v237, -v236
	ds_write_b32 v209, v237
	s_or_b64 exec, exec, s[78:79]
	v_add_f32_e32 v202, v202, v236
	v_xor_b32_e32 v96, 0x80000000, v202
	v_sub_f32_e32 v143, v143, v236
	v_sub_f32_e32 v142, v142, v236
	v_sub_f32_e32 v141, v141, v236
	v_sub_f32_e32 v140, v140, v236
	v_sub_f32_e32 v139, v139, v236
	v_sub_f32_e32 v138, v138, v236
	v_sub_f32_e32 v137, v137, v236
	v_sub_f32_e32 v136, v136, v236
	v_sub_f32_e32 v135, v135, v236
	v_sub_f32_e32 v134, v134, v236
	v_sub_f32_e32 v133, v133, v236
	v_sub_f32_e32 v132, v132, v236
	v_sub_f32_e32 v131, v131, v236
	v_sub_f32_e32 v130, v130, v236
	v_sub_f32_e32 v129, v129, v236
	v_sub_f32_e32 v128, v128, v236
	v_sub_f32_e32 v127, v127, v236
	v_sub_f32_e32 v126, v126, v236
	v_sub_f32_e32 v125, v125, v236
	v_sub_f32_e32 v124, v124, v236
	v_sub_f32_e32 v123, v123, v236
	v_sub_f32_e32 v122, v122, v236
	v_sub_f32_e32 v121, v121, v236
	v_sub_f32_e32 v120, v120, v236
	v_sub_f32_e32 v119, v119, v236
	v_sub_f32_e32 v118, v118, v236
	v_sub_f32_e32 v117, v117, v236
	v_sub_f32_e32 v116, v116, v236
	v_sub_f32_e32 v115, v115, v236
	v_sub_f32_e32 v114, v114, v236
	v_sub_f32_e32 v113, v113, v236
	v_sub_f32_e32 v112, v112, v236
	v_mov_b32_e32 v97, v96
	v_mov_b32_e32 v98, v96
	v_mov_b32_e32 v99, v96
	v_mov_b32_e32 v100, v96
	v_mov_b32_e32 v101, v96
	v_mov_b32_e32 v102, v96
	v_mov_b32_e32 v103, v96
	v_mov_b32_e32 v104, v96
	v_mov_b32_e32 v105, v96
	v_mov_b32_e32 v106, v96
	v_mov_b32_e32 v107, v96
	v_mov_b32_e32 v108, v96
	v_mov_b32_e32 v109, v96
	v_mov_b32_e32 v110, v96
	v_mov_b32_e32 v111, v96
.LBB0_754:
	v_exp_f32_e32 v80, v128
	v_exp_f32_e32 v81, v129
	v_exp_f32_e32 v64, v112
	v_mfma_f32_32x32x16_bf16 v[48:63], v[176:179], v[248:251], v[48:63]
	ds_read_b64_tr_b16 v[2:3], v0 offset:4096
	ds_read_b64_tr_b16 v[4:5], v0 offset:5120
	ds_read_b64_tr_b16 v[6:7], v14 offset:4096
	ds_read_b64_tr_b16 v[8:9], v14 offset:5120
	v_exp_f32_e32 v82, v130
	v_exp_f32_e32 v65, v113
	v_exp_f32_e32 v66, v114
	v_exp_f32_e32 v83, v131
	s_waitcnt lgkmcnt(6)
	v_mfma_f32_32x32x16_bf16 v[32:47], v[176:179], v[212:215], v[32:47]
	v_exp_f32_e32 v67, v115
	v_exp_f32_e32 v84, v132
	v_exp_f32_e32 v85, v133
	v_exp_f32_e32 v68, v116
	s_waitcnt lgkmcnt(4)
	v_mfma_f32_32x32x16_bf16 v[16:31], v[176:179], v[216:219], v[16:31]
	v_exp_f32_e32 v86, v134
	v_exp_f32_e32 v69, v117
	v_exp_f32_e32 v70, v118
	v_exp_f32_e32 v87, v135
	v_mfma_f32_32x32x16_bf16 v[48:63], v[180:183], v[248:251], v[48:63]
	ds_read_b64_tr_b16 v[228:229], v0 offset:6144
	ds_read_b64_tr_b16 v[230:231], v0 offset:7168
	ds_read_b64_tr_b16 v[232:233], v14 offset:6144
	ds_read_b64_tr_b16 v[234:235], v14 offset:7168
	v_exp_f32_e32 v71, v119
	v_exp_f32_e32 v88, v136
	v_exp_f32_e32 v89, v137
	s_waitcnt lgkmcnt(6)
	v_mfma_f32_32x32x16_bf16 v[32:47], v[180:183], v[2:5], v[32:47]
	v_exp_f32_e32 v72, v120
	v_exp_f32_e32 v90, v138
	v_exp_f32_e32 v73, v121
	s_waitcnt lgkmcnt(4)
	v_mfma_f32_32x32x16_bf16 v[16:31], v[180:183], v[6:9], v[16:31]
	v_exp_f32_e32 v74, v122
	v_exp_f32_e32 v91, v139
	v_exp_f32_e32 v75, v123
	v_mfma_f32_32x32x16_bf16 v[48:63], v[168:171], v[248:251], v[48:63]
	v_exp_f32_e32 v92, v140
	v_exp_f32_e32 v93, v141
	v_exp_f32_e32 v76, v124
	s_waitcnt lgkmcnt(2)
	v_mfma_f32_32x32x16_bf16 v[32:47], v[168:171], v[228:231], v[32:47]
	v_exp_f32_e32 v94, v142
	v_exp_f32_e32 v77, v125
	v_exp_f32_e32 v78, v126
	s_waitcnt lgkmcnt(0)
	v_mfma_f32_32x32x16_bf16 v[16:31], v[168:171], v[232:235], v[16:31]
	v_exp_f32_e32 v95, v143
	v_exp_f32_e32 v79, v127
	s_andn2_b64 vcc, exec, s[72:73]
	s_cbranch_vccnz .LBB0_756
	s_waitcnt lgkmcnt(0)
	ds_read_b128 v[2:5], v210 offset:96
	ds_read_b128 v[6:9], v210 offset:64
	ds_read_b128 v[10:13], v210 offset:32
	ds_read_b128 v[112:115], v210
	s_waitcnt lgkmcnt(0)
	s_waitcnt lgkmcnt(3)
	v_pk_mul_f32 v[46:47], v[46:47], v[4:5]
	s_waitcnt lgkmcnt(2)
	v_pk_mul_f32 v[42:43], v[42:43], v[8:9]
	s_waitcnt lgkmcnt(1)
	v_pk_mul_f32 v[38:39], v[38:39], v[12:13]
	s_waitcnt lgkmcnt(0)
	v_pk_mul_f32 v[34:35], v[34:35], v[114:115]
	v_pk_mul_f32 v[44:45], v[44:45], v[2:3]
	v_pk_mul_f32 v[40:41], v[40:41], v[6:7]
	v_pk_mul_f32 v[36:37], v[36:37], v[10:11]
	v_pk_mul_f32 v[32:33], v[32:33], v[112:113]
	v_pk_mul_f32 v[30:31], v[30:31], v[4:5]
	v_pk_mul_f32 v[26:27], v[26:27], v[8:9]
	v_pk_mul_f32 v[22:23], v[22:23], v[12:13]
	v_pk_mul_f32 v[18:19], v[18:19], v[114:115]
	v_pk_mul_f32 v[28:29], v[28:29], v[2:3]
	v_pk_mul_f32 v[24:25], v[24:25], v[6:7]
	v_pk_mul_f32 v[20:21], v[20:21], v[10:11]
	v_pk_mul_f32 v[16:17], v[16:17], v[112:113]
	v_pk_mul_f32 v[62:63], v[62:63], v[4:5]
	v_pk_mul_f32 v[58:59], v[58:59], v[8:9]
	v_pk_mul_f32 v[54:55], v[54:55], v[12:13]
	v_pk_mul_f32 v[50:51], v[50:51], v[114:115]
	v_pk_mul_f32 v[60:61], v[60:61], v[2:3]
	v_pk_mul_f32 v[56:57], v[56:57], v[6:7]
	v_pk_mul_f32 v[52:53], v[52:53], v[10:11]
	v_pk_mul_f32 v[48:49], v[48:49], v[112:113]

; __global__ void __launch_bounds__(512, 2) mega_fwd(Args a) {
	.amdhsa_kernel _Z8mega_fwd4Args
		.amdhsa_group_segment_fixed_size 0
		.amdhsa_private_segment_fixed_size 0
		.amdhsa_kernarg_size 464
		.amdhsa_user_sgpr_count 2
		.amdhsa_user_sgpr_dispatch_ptr 0
		.amdhsa_user_sgpr_queue_ptr 0
		.amdhsa_user_sgpr_kernarg_segment_ptr 1
		.amdhsa_user_sgpr_dispatch_id 0
		.amdhsa_user_sgpr_kernarg_preload_length 0
		.amdhsa_user_sgpr_kernarg_preload_offset 0
		.amdhsa_user_sgpr_private_segment_size 0
		.amdhsa_uses_dynamic_stack 0
		.amdhsa_enable_private_segment 0
		.amdhsa_system_sgpr_workgroup_id_x 1
		.amdhsa_system_sgpr_workgroup_id_y 0
		.amdhsa_system_sgpr_workgroup_id_z 0
		.amdhsa_system_sgpr_workgroup_info 0
		.amdhsa_system_vgpr_workitem_id 2
		.amdhsa_next_free_vgpr 252
		.amdhsa_next_free_sgpr 98
		.amdhsa_accum_offset 252
		.amdhsa_reserve_vcc 1
		.amdhsa_float_round_mode_32 0
		.amdhsa_float_round_mode_16_64 0
		.amdhsa_float_denorm_mode_32 3
		.amdhsa_float_denorm_mode_16_64 3
		.amdhsa_dx10_clamp 1
		.amdhsa_ieee_mode 1
		.amdhsa_fp16_overflow 0
		.amdhsa_tg_split 0
		.amdhsa_exception_fp_ieee_invalid_op 0
		.amdhsa_exception_fp_denorm_src 0
		.amdhsa_exception_fp_ieee_div_zero 0
		.amdhsa_exception_fp_ieee_overflow 0
		.amdhsa_exception_fp_ieee_underflow 0
		.amdhsa_exception_fp_ieee_inexact 0
		.amdhsa_exception_int_div_zero 0
	.end_amdhsa_kernel

; __global__ void __launch_bounds__(512, 2) mega_fwd(Args a) {
amdhsa.kernels:
  - .agpr_count:     0
    .args:
      - .offset:         0
        .size:           208
        .value_kind:     by_value
      - .offset:         208
        .size:           4
        .value_kind:     hidden_block_count_x
      - .offset:         212
        .size:           4
        .value_kind:     hidden_block_count_y
      - .offset:         216
        .size:           4
        .value_kind:     hidden_block_count_z
      - .offset:         220
        .size:           2
        .value_kind:     hidden_group_size_x
      - .offset:         222
        .size:           2
        .value_kind:     hidden_group_size_y
      - .offset:         224
        .size:           2
        .value_kind:     hidden_group_size_z
      - .offset:         226
        .size:           2
        .value_kind:     hidden_remainder_x
      - .offset:         228
        .size:           2
        .value_kind:     hidden_remainder_y
      - .offset:         230
        .size:           2
        .value_kind:     hidden_remainder_z
      - .offset:         248
        .size:           8
        .value_kind:     hidden_global_offset_x
      - .offset:         256
        .size:           8
        .value_kind:     hidden_global_offset_y
      - .offset:         264
        .size:           8
        .value_kind:     hidden_global_offset_z
      - .offset:         272
        .size:           2
        .value_kind:     hidden_grid_dims
      - .offset:         296
        .size:           8
        .value_kind:     hidden_multigrid_sync_arg
      - .offset:         328
        .size:           4
        .value_kind:     hidden_dynamic_lds_size
    .group_segment_fixed_size: 0
    .kernarg_segment_align: 8
    .kernarg_segment_size: 464
    .language:       OpenCL C
    .language_version:
      - 2
      - 0
    .max_flat_workgroup_size: 512
    .name:           _Z8mega_fwd4Args
    .private_segment_fixed_size: 0
    .sgpr_count:     104
    .sgpr_spill_count: 131
    .symbol:         _Z8mega_fwd4Args.kd
    .uniform_work_group_size: 1
    .uses_dynamic_stack: false
    .vgpr_count:     252
    .vgpr_spill_count: 0
    .wavefront_size: 64
